# speedup vs baseline: 1.0018x; 1.0018x over previous
; __device__ __forceinline__ void mlstm_item(const int tid0, const P& p, int item, char* lds) {
;     ...
;         m = bL + Mlast;
;         __syncthreads();
;     }
.LBB0_164:
	s_or_b64 exec, exec, s[6:7]
	s_add_i32 s28, s28, -1
	s_add_i32 s30, s30, 1
	v_add_f32_e32 v193, v188, v190
	s_cmp_eq_u32 s28, -2
	s_waitcnt vmcnt(0)
	v_mov_b32_e32 v188, v71
	s_waitcnt lgkmcnt(0)
	s_barrier
	s_cbranch_scc1 .LBB0_118

; __device__ __forceinline__ unsigned cvtpk(float lo, float hi) { unsigned r; asm volatile("v_cvt_pk_bf16_f32 %0, %1, %2" : "=v"(r) : "v"(lo), "v"(hi)); return r; }
; __device__ __forceinline__ float fexp(float x) { return __builtin_amdgcn_exp2f(x * 1.4426950408889634f); }
; __device__ __forceinline__ void mlstm_item(const int tid0, const P& p, int item, char* lds) {
;     ...
;         const float wcf = fexp(m - Mlast);
; #pragma unroll
;         for (int r = 0; r < 16; ++r) { ct0[r] *= wcf; ct1[r] *= wcf; nacc[r] *= wcf; }
;     ...
;         MSTEP(0, 0); MSTEP(0, 1); MSTEP(0, 2); MSTEP(0, 3); MSTEP(16384, 0); MSTEP(16384, 1); MSTEP(16384, 2); MSTEP(16384, 3);
;     ...
; #pragma unroll
;         for (int g = 0; g < 4; ++g) { const int kb = (32 * w4 + 8 * g + 4 * hi) * 2;
;             u32x2 w0; w0.x = cvtpk(ct0[4 * g], ct0[4 * g + 1]); w0.y = cvtpk(ct0[4 * g + 2], ct0[4 * g + 3]);
;             u32x2 w1; w1.x = cvtpk(ct1[4 * g], ct1[4 * g + 1]); w1.y = cvtpk(ct1[4 * g + 2], ct1[4 * g + 3]);
;             *(u32x2*)(Cs + KSWZ(64 * vh + r32, kb)) = w0; *(u32x2*)(Cs + KSWZ(64 * vh + 32 + r32, kb)) = w1; }
.LBB0_308:
	v_sub_f32_e32 v50, v193, v190
	v_mul_f32_e32 v50, 0x3fb8aa3b, v50
	v_add_u32_e32 v88, s48, v204
	v_exp_f32_e32 v70, v50
	s_barrier
	ds_read_b64_tr_b16 v[50:51], v88 offset:0
	ds_read_b64_tr_b16 v[52:53], v88 offset:0x800
	ds_read_b64_tr_b16 v[54:55], v203 offset:0
	ds_read_b64_tr_b16 v[56:57], v203 offset:0x800
	ds_read_b64_tr_b16 v[58:59], v203 offset:0x200
	ds_read_b64_tr_b16 v[60:61], v203 offset:0xa00
	s_waitcnt lgkmcnt(0)
	v_pk_mul_f32 v[16:17], v[16:17], v[70:71] op_sel_hi:[1,0]
	v_pk_mul_f32 v[14:15], v[14:15], v[70:71] op_sel_hi:[1,0]
	v_pk_mul_f32 v[12:13], v[12:13], v[70:71] op_sel_hi:[1,0]
	v_pk_mul_f32 v[10:11], v[10:11], v[70:71] op_sel_hi:[1,0]
	v_pk_mul_f32 v[8:9], v[8:9], v[70:71] op_sel_hi:[1,0]
	v_pk_mul_f32 v[6:7], v[6:7], v[70:71] op_sel_hi:[1,0]
	v_pk_mul_f32 v[4:5], v[4:5], v[70:71] op_sel_hi:[1,0]
	v_pk_mul_f32 v[2:3], v[2:3], v[70:71] op_sel_hi:[1,0]
	v_pk_mul_f32 v[32:33], v[32:33], v[70:71] op_sel_hi:[1,0]
	v_pk_mul_f32 v[30:31], v[30:31], v[70:71] op_sel_hi:[1,0]
	v_pk_mul_f32 v[28:29], v[28:29], v[70:71] op_sel_hi:[1,0]
	v_pk_mul_f32 v[26:27], v[26:27], v[70:71] op_sel_hi:[1,0]
	v_pk_mul_f32 v[24:25], v[24:25], v[70:71] op_sel_hi:[1,0]
	v_pk_mul_f32 v[22:23], v[22:23], v[70:71] op_sel_hi:[1,0]
	v_pk_mul_f32 v[20:21], v[20:21], v[70:71] op_sel_hi:[1,0]
	v_pk_mul_f32 v[18:19], v[18:19], v[70:71] op_sel_hi:[1,0]
	v_mfma_f32_32x32x16_bf16 v[2:17], v[50:53], v[54:57], v[2:17]
	ds_read_b64_tr_b16 v[54:55], v88 offset:0x1000
	ds_read_b64_tr_b16 v[56:57], v88 offset:0x1800
	s_nop 0
	v_mfma_f32_32x32x16_bf16 v[18:33], v[50:53], v[58:61], v[18:33]
	ds_read_b64_tr_b16 v[58:59], v203 offset:0x1000
	ds_read_b64_tr_b16 v[60:61], v203 offset:0x1800
	ds_read_b64_tr_b16 v[62:63], v203 offset:0x1200
	ds_read_b64_tr_b16 v[64:65], v203 offset:0x1a00
	s_waitcnt lgkmcnt(0)
	s_nop 0
	v_mfma_f32_32x32x16_bf16 v[2:17], v[54:57], v[58:61], v[2:17]
	ds_read_b64_tr_b16 v[58:59], v88 offset:0x2000
	ds_read_b64_tr_b16 v[60:61], v88 offset:0x2800
	v_mfma_f32_32x32x16_bf16 v[18:33], v[54:57], v[62:65], v[18:33]
	ds_read_b64_tr_b16 v[62:63], v203 offset:0x2000
	ds_read_b64_tr_b16 v[64:65], v203 offset:0x2800
	ds_read_b64_tr_b16 v[66:67], v203 offset:0x2200
	ds_read_b64_tr_b16 v[68:69], v203 offset:0x2a00
	s_waitcnt lgkmcnt(0)
	s_nop 0
	v_mfma_f32_32x32x16_bf16 v[2:17], v[58:61], v[62:65], v[2:17]
	ds_read_b64_tr_b16 v[62:63], v88 offset:0x3000
	ds_read_b64_tr_b16 v[64:65], v88 offset:0x3800
	v_mfma_f32_32x32x16_bf16 v[18:33], v[58:61], v[66:69], v[18:33]
	ds_read_b64_tr_b16 v[66:67], v203 offset:0x3000
	ds_read_b64_tr_b16 v[68:69], v203 offset:0x3800
	ds_read_b64_tr_b16 v[72:73], v203 offset:0x3200
	ds_read_b64_tr_b16 v[74:75], v203 offset:0x3a00
	s_waitcnt lgkmcnt(0)
	s_nop 0
	v_mfma_f32_32x32x16_bf16 v[2:17], v[62:65], v[66:69], v[2:17]
	ds_read_b64_tr_b16 v[66:67], v88 offset:0x4000
	ds_read_b64_tr_b16 v[68:69], v88 offset:0x4800
	v_mfma_f32_32x32x16_bf16 v[18:33], v[62:65], v[72:75], v[18:33]
	ds_read_b64_tr_b16 v[72:73], v203 offset:0x4000
	ds_read_b64_tr_b16 v[74:75], v203 offset:0x4800
	ds_read_b64_tr_b16 v[76:77], v203 offset:0x4200
	ds_read_b64_tr_b16 v[78:79], v203 offset:0x4a00
	s_waitcnt lgkmcnt(0)
	s_nop 0
	v_mfma_f32_32x32x16_bf16 v[2:17], v[66:69], v[72:75], v[2:17]
	ds_read_b64_tr_b16 v[72:73], v88 offset:0x5000
	ds_read_b64_tr_b16 v[74:75], v88 offset:0x5800
	v_mfma_f32_32x32x16_bf16 v[18:33], v[66:69], v[76:79], v[18:33]
	ds_read_b64_tr_b16 v[76:77], v203 offset:0x5000
	ds_read_b64_tr_b16 v[78:79], v203 offset:0x5800
	ds_read_b64_tr_b16 v[80:81], v203 offset:0x5200
	ds_read_b64_tr_b16 v[82:83], v203 offset:0x5a00
	s_waitcnt lgkmcnt(0)
	s_nop 0
	v_mfma_f32_32x32x16_bf16 v[2:17], v[72:75], v[76:79], v[2:17]
	ds_read_b64_tr_b16 v[76:77], v88 offset:0x6000
	ds_read_b64_tr_b16 v[78:79], v88 offset:0x6800
	v_mfma_f32_32x32x16_bf16 v[18:33], v[72:75], v[80:83], v[18:33]
	ds_read_b64_tr_b16 v[80:81], v203 offset:0x6000
	ds_read_b64_tr_b16 v[82:83], v203 offset:0x6800
	ds_read_b64_tr_b16 v[84:85], v203 offset:0x6200
	ds_read_b64_tr_b16 v[86:87], v203 offset:0x6a00
	s_waitcnt lgkmcnt(0)
	s_nop 0
	v_mfma_f32_32x32x16_bf16 v[2:17], v[76:79], v[80:83], v[2:17]
	ds_read_b64_tr_b16 v[80:81], v88 offset:0x7000
	ds_read_b64_tr_b16 v[82:83], v88 offset:0x7800
	v_mfma_f32_32x32x16_bf16 v[18:33], v[76:79], v[84:87], v[18:33]
	ds_read_b64_tr_b16 v[84:85], v203 offset:0x7000
	ds_read_b64_tr_b16 v[86:87], v203 offset:0x7800
	ds_read_b64_tr_b16 v[88:89], v203 offset:0x7200
	ds_read_b64_tr_b16 v[90:91], v203 offset:0x7a00
	s_waitcnt lgkmcnt(0)
	s_mov_b32 s22, s20
	s_mov_b32 s23, s20
	v_mfma_f32_32x32x16_bf16 v[2:17], v[80:83], v[84:87], v[2:17]
	s_mov_b32 s21, s20
	v_mov_b64_e32 v[86:87], s[22:23]
	v_mul_f32_e64 v48, v48, v70
	v_mul_f32_e64 v49, v49, v70
	v_mul_f32_e64 v46, v46, v70
	v_mul_f32_e64 v47, v47, v70
	v_pk_mul_f32 v[44:45], v[44:45], v[70:71] op_sel_hi:[1,0]
	v_pk_mul_f32 v[42:43], v[42:43], v[70:71] op_sel_hi:[1,0]
	v_pk_mul_f32 v[40:41], v[40:41], v[70:71] op_sel_hi:[1,0]
	v_pk_mul_f32 v[38:39], v[38:39], v[70:71] op_sel_hi:[1,0]
	v_pk_mul_f32 v[36:37], v[36:37], v[70:71] op_sel_hi:[1,0]
	v_pk_mul_f32 v[34:35], v[34:35], v[70:71] op_sel_hi:[1,0]
	v_mov_b64_e32 v[84:85], s[20:21]
	v_mfma_f32_32x32x16_bf16 v[18:33], v[80:83], v[88:91], v[18:33]
	v_cmp_eq_u32_e32 vcc, 0, v191
	s_and_b64 s[8:9], s[84:85], vcc
	v_mfma_f32_32x32x16_bf16 v[34:49], v[50:53], v[84:87], v[34:49]
	v_cvt_pk_bf16_f32 v50, v2, v3
	v_cvt_pk_bf16_f32 v51, v4, v5
	v_cvt_pk_bf16_f32 v52, v18, v19
	v_cvt_pk_bf16_f32 v53, v20, v21
	v_mfma_f32_32x32x16_bf16 v[34:49], v[54:57], v[84:87], v[34:49]
	v_or_b32_e32 v54, s15, v192
	v_xad_u32 v55, v54, v194, v195
	ds_write2st64_b64 v55, v[50:51], v[52:53] offset1:16
	v_or_b32_e32 v55, 16, v54
	v_xad_u32 v55, v55, v194, v195
	v_cvt_pk_bf16_f32 v50, v6, v7
	v_cvt_pk_bf16_f32 v51, v8, v9
	v_mfma_f32_32x32x16_bf16 v[34:49], v[58:61], v[84:87], v[34:49]
	v_cvt_pk_bf16_f32 v52, v22, v23
	v_cvt_pk_bf16_f32 v53, v24, v25
	ds_write2st64_b64 v55, v[50:51], v[52:53] offset1:16
	v_or_b32_e32 v55, 32, v54
	v_or_b32_e32 v54, 48, v54
	v_cvt_pk_bf16_f32 v50, v10, v11
	v_cvt_pk_bf16_f32 v51, v12, v13
	v_mfma_f32_32x32x16_bf16 v[34:49], v[62:65], v[84:87], v[34:49]
	v_cvt_pk_bf16_f32 v52, v26, v27
	v_cvt_pk_bf16_f32 v53, v28, v29
	v_xad_u32 v55, v55, v194, v195
	v_xad_u32 v54, v54, v194, v195
	ds_write2st64_b64 v55, v[50:51], v[52:53] offset1:16
	v_cvt_pk_bf16_f32 v50, v14, v15
	v_cvt_pk_bf16_f32 v51, v16, v17
	v_mfma_f32_32x32x16_bf16 v[34:49], v[66:69], v[84:87], v[34:49]
	v_cvt_pk_bf16_f32 v52, v30, v31
	v_cvt_pk_bf16_f32 v53, v32, v33
	ds_write2st64_b64 v54, v[50:51], v[52:53] offset1:16
	v_mfma_f32_32x32x16_bf16 v[34:49], v[72:75], v[84:87], v[34:49]
	v_mfma_f32_32x32x16_bf16 v[34:49], v[76:79], v[84:87], v[34:49]
	v_mfma_f32_32x32x16_bf16 v[34:49], v[80:83], v[84:87], v[34:49]
	s_and_saveexec_b64 s[6:7], s[8:9]
	s_cbranch_execz .LBB0_164
; __device__ __forceinline__ int crow(int r, int hi) { return (r & 3) + 8 * (r >> 2) + 4 * hi; }
; __device__ __forceinline__ void mlstm_item(const int tid0, const P& p, int item, char* lds) {
;     ...
;         if (vh == 0 && r32 == 0) {
; #pragma unroll
;             for (int r = 0; r < 16; ++r) nvec[32 * w4 + crow(r, hi)] = nacc[r]; }
	v_add_u32_e32 v0, s14, v0
	s_nop 8
	ds_write_b128 v0, v[34:37]
	ds_write_b128 v0, v[38:41] offset:32
	ds_write_b128 v0, v[42:45] offset:64
	ds_write_b128 v0, v[46:49] offset:96
	s_branch .LBB0_164
